# P4 attention: depth-2 gather prefetch, QK/PV LDS read pipelining, streamlined softmax, idx-row prefetch across items
# speedup vs baseline: 1.0412x; 1.0140x over previous
; __device__ __forceinline__ void p4_attn(const Params& p, unsigned char* lds, int bid, int nb, bool dry) {
;     ...
;   const int lane = tid & 63, wid = __builtin_amdgcn_readfirstlane(tid >> 6), g = lane >> 4, r16 = lane & 15;
;   for (int i = tid; i < 129 * 32; i += 512) {
;     const int d = i >> 5, hd = i & 31; int bucket = d;
;     if (d >= 16) { bucket = 16 + (d >= 19) + (d >= 21) + (d >= 24) + (d >= 27) + (d >= 31) + (d >= 35) + (d >= 40) + (d >= 46) + (d >= 52) + (d >= 59) + (d >= 67) + (d >= 77) + (d >= 87) + (d >= 99) + (d >= 113); }
;     biasd[i] = ((const float*)(p.ws + OFF_SMALL))[SM_RELB + bucket * 32 + hd] * LOG2E;
;   }
;   LAS unsigned* pcnt = (LAS unsigned*)((LAS unsigned char*)lds + 2 * CBUF + 129 * 32 * 4 + 2048) + (wid >> 1);
;   if (tid < 4) ((LAS unsigned*)((LAS unsigned char*)lds + 2 * CBUF + 129 * 32 * 4 + 2048))[tid] = 0u;
;   __syncthreads();
;   unsigned epoch = 0u;
;   const int tok = wid >> 1, hw = wid & 1, head = hw * 16 + r16;
;   const float SC = 0.08838834764831845f * LOG2E;
;   const int qoff = 16 * (g ^ (r16 >> 3));
;   const int q4 = r16 >> 2, pp = r16 & 3;
;   const int troff = (4 * g + q4) * CROW + 16 * ((pp >> 1) ^ (g >> 1)) + 8 * (pp & 1);
;   const int wrow = 16 * hw + 8 * (lane >> 5), wch = lane & 31;
;   for (int round = 0; round * nb < T / 4; ++round) {
;     const int item = round * nb + (bid + round * 37) % nb;
;     const int tg0 = item * 4, b = tg0 >> 11, t0 = tg0 & 2047, t = t0 + tok, tg = tg0 + tok;
;     const int nk = min(t + 1, 256), nkmax = min(t0 + 4, 256), nch = (nkmax + 31) >> 5;
;     ((LAS unsigned*)idxs)[tid] = ((const unsigned*)(idxg + (size_t)tg0 * 256))[tid];
;     unsigned char* qrow = QL + (size_t)tg * 8192 + head * 256;
;     bf16x8 qB[8];
; #pragma unroll
;     for (int s = 0; s < 8; ++s) { const u32x2 qw = *(const u32x2*)(qrow + 32 * s + 8 * g);
;       typedef float f32x2v __attribute__((ext_vector_type(2)));
;       const f32x2v a0 = __builtin_amdgcn_cvt_pk_f32_fp8(qw[0], false), a1 = __builtin_amdgcn_cvt_pk_f32_fp8(qw[0], true), a2 = __builtin_amdgcn_cvt_pk_f32_fp8(qw[1], false), a3 = __builtin_amdgcn_cvt_pk_f32_fp8(qw[1], true);
;       u32x4 pw; pw[0] = cvt_pk_bf16(a0[0], a0[1]); pw[1] = cvt_pk_bf16(a1[0], a1[1]); pw[2] = cvt_pk_bf16(a2[0], a2[1]); pw[3] = cvt_pk_bf16(a3[0], a3[1]);
;       union { u32x4 u; bf16x8 v; } cv; cv.u = pw; qB[s] = cv.v; }
.LBB0_988:
	s_or_b64 exec, exec, s[4:5]
	v_cmp_gt_i32_e32 vcc, 4, v2
	s_and_saveexec_b64 s[4:5], vcc
	v_add_u32_e32 v0, 0x26880, v0
	v_mov_b32_e32 v1, 0
	ds_write_b32 v0, v1
	s_or_b64 exec, exec, s[4:5]
	v_bfe_u32 v5, v2, 4, 2
	v_bfe_u32 v0, v2, 3, 1
	v_xor_b32_e32 v0, v5, v0
	v_lshlrev_b32_e32 v162, 4, v0
	v_bfe_u32 v0, v2, 2, 2
	v_lshlrev_b32_e32 v148, 2, v5
	v_or_b32_e32 v0, v148, v0
	s_ashr_i32 s0, s3, 7
	s_lshr_b32 s3, s3, 2
	v_mul_u32_u24_e32 v163, 0x220, v0
	v_lshrrev_b32_e32 v0, 1, v2
	v_bfe_u32 v8, v2, 5, 1
	v_and_b32_e32 v6, 15, v2
	s_and_b32 s3, s3, 16
	v_bitop3_b32 v0, v0, v8, 1 bitop3:0x6c
	v_readlane_b32 s4, v254, 36
	v_or_b32_e32 v7, s3, v6
	v_lshlrev_b32_e32 v164, 4, v0
	v_lshlrev_b32_e32 v0, 3, v2
	v_ashrrev_i32_e32 v3, 31, v2
	v_readlane_b32 s5, v254, 37
	v_and_b32_e32 v165, 8, v0
	v_and_b32_e32 v10, 31, v2
	v_lshl_add_u64 v[150:151], v[2:3], 2, s[4:5]
	v_lshlrev_b32_e32 v0, 8, v7
	v_mov_b32_e32 v1, 0
	v_readlane_b32 s4, v254, 42
	v_lshl_add_u64 v[152:153], s[92:93], 0, v[0:1]
	v_lshlrev_b32_e32 v0, 4, v10
	v_readlane_b32 s5, v254, 43
	v_lshl_or_b32 v9, v8, 3, s3
	s_add_i32 s3, 0, 0x26080
	v_lshl_add_u64 v[156:157], s[4:5], 0, v[0:1]
	s_lshl_b32 s4, s0, 9
	s_lshl_b32 s2, s0, 2
	v_lshl_add_u32 v166, v2, 2, s3
	s_add_i32 s3, s3, s4
	s_mul_i32 s4, s0, 0x4400
	v_bitop3_b32 v0, v8, v2, 31 bitop3:0x78
	s_add_i32 s2, s2, 0
	v_and_b32_e32 v4, 63, v2
	s_add_i32 s5, s4, 0
	v_lshlrev_b32_e32 v0, 4, v0
	s_add_i32 s4, 0, 0x22000
	v_mul_u32_u24_e32 v2, 0x220, v9
	s_mov_b32 s1, 0
	s_add_i32 s2, s2, 0x26880
	v_lshlrev_b32_e32 v154, 3, v5
	v_mov_b32_e32 v155, v1
	v_cmp_eq_u32_e64 s[8:9], 0, v4
	v_lshl_add_u32 v167, v9, 1, s3
	v_mul_u32_u24_e32 v168, 0x220, v6
	v_lshl_add_u32 v169, v7, 2, s4
	v_mov_b32_e32 v149, v1
	v_add3_u32 v170, s5, v0, v2
	s_movk_i32 s16, 0x80
	s_mov_b32 s4, 0x3e0293ee
	s_mov_b32 s17, 0xf149f2ca
	s_mov_b32 s18, 0x41800000
	v_mov_b32_e32 v171, 9
	v_mov_b32_e32 v172, 0x80
	v_mov_b32_e32 v173, 0xf149f2ca
	s_mov_b32 s10, 0
	s_mov_b32 s19, 0
	s_mov_b32 s20, 0
	s_lshl_b32 s28, s88, 11
	s_mov_b32 s29, 0
	v_lshl_add_u64 v[2:3], v[150:151], 0, s[28:29]
	global_load_dword v255, v[2:3], off
	s_waitcnt vmcnt(0)
	s_waitcnt lgkmcnt(0)
	s_barrier
.LBB0_991:
	s_mul_i32 s11, s20, 37
	s_add_i32 s11, s11, s88
	s_ashr_i32 s12, s11, 31
	s_abs_i32 s11, s11
	v_readlane_b32 s13, v254, 32
	s_mul_hi_u32 s13, s11, s13
	v_readlane_b32 s14, v254, 33
	s_mul_i32 s13, s13, s14
	s_sub_i32 s11, s11, s13
	s_sub_i32 s13, s11, s14
	s_cmp_ge_u32 s11, s14
	s_cselect_b32 s11, s13, s11
	s_sub_i32 s13, s11, s14
	s_cmp_ge_u32 s11, s14
	s_cselect_b32 s11, s13, s11
	s_xor_b32 s11, s11, s12
	s_sub_i32 s22, s11, s12
	s_add_i32 s21, s22, s10
	s_lshl_b32 s10, s21, 2
	s_add_i32 s12, s10, s0
	s_ashr_i32 s11, s10, 31
	s_ashr_i32 s13, s12, 31
	s_lshl_b64 s[14:15], s[10:11], 9
	s_lshl_b64 s[12:13], s[12:13], 13
	v_lshl_add_u64 v[158:159], v[152:153], 0, s[12:13]
	v_lshl_add_u64 v[4:5], v[158:159], 0, v[154:155]
	s_waitcnt vmcnt(16)
	ds_write_b32 v166, v255
	global_load_dwordx2 v[218:219], v[4:5], off
	global_load_dwordx2 v[220:221], v[4:5], off offset:32
	global_load_dwordx2 v[222:223], v[4:5], off offset:64
	global_load_dwordx2 v[224:225], v[4:5], off offset:96
	global_load_dwordx2 v[226:227], v[4:5], off offset:128
	global_load_dwordx2 v[228:229], v[4:5], off offset:160
	global_load_dwordx2 v[230:231], v[4:5], off offset:192
	global_load_dwordx2 v[232:233], v[4:5], off offset:224
	s_and_saveexec_b64 s[12:13], s[8:9]
	s_cbranch_execz .LBB0_994
	s_mov_b64 s[14:15], exec
	v_mbcnt_lo_u32_b32 v0, s14, 0
	v_mbcnt_hi_u32_b32 v0, s15, v0
	v_cmp_eq_u32_e32 vcc, 0, v0
	s_and_b64 s[24:25], exec, vcc
	s_mov_b64 exec, s[24:25]
	s_bcnt1_i32_b64 s11, s[14:15]
	v_mov_b32_e32 v0, s2
	v_mov_b32_e32 v2, s11
	ds_add_u32 v0, v2

; #define LAS __attribute__((address_space(3)))
; __device__ __forceinline__ unsigned cvt_pk_bf16(float lo, float hi) { unsigned r; asm("v_cvt_pk_bf16_f32 %0, %1, %2" : "=v"(r) : "v"(lo), "v"(hi)); return r; }
; #define P4_LOAD(ch) do { const u32x4 kk_ = *(const LAS u32x4*)(idxs + tok * 256 + (ch) * 32 + wrow); \
;       _Pragma("unroll") for (int i = 0; i < 8; ++i) { \
;       const int key = (int)((kk_[i >> 1] >> (16 * (i & 1))) & 0xffffu); stg[i] = *(const u32x4*)(cbase + (size_t)key * 256); } } while (0)
; #define P4_WRITE(bufp) do { _Pragma("unroll") for (int i = 0; i < 8; ++i) \
;       *(LAS u32x4*)((bufp) + (wrow + i) * CROW + 16 * (wch ^ (lane >> 5))) = stg[i]; } while (0)
; __device__ __forceinline__ void p4_attn(const Params& p, unsigned char* lds, int bid, int nb, bool dry) {
;     ...
;     const int item = round * nb + (bid + round * 37) % nb;
;     const int tg0 = item * 4, b = tg0 >> 11, t0 = tg0 & 2047, t = t0 + tok, tg = tg0 + tok;
;     const int nk = min(t + 1, 256), nkmax = min(t0 + 4, 256), nch = (nkmax + 31) >> 5;
;     ((LAS unsigned*)idxs)[tid] = ((const unsigned*)(idxg + (size_t)tg0 * 256))[tid];
;     unsigned char* qrow = QL + (size_t)tg * 8192 + head * 256;
;     bf16x8 qB[8];
; #pragma unroll
;     for (int s = 0; s < 8; ++s) { const u32x2 qw = *(const u32x2*)(qrow + 32 * s + 8 * g);
;       typedef float f32x2v __attribute__((ext_vector_type(2)));
;       const f32x2v a0 = __builtin_amdgcn_cvt_pk_f32_fp8(qw[0], false), a1 = __builtin_amdgcn_cvt_pk_f32_fp8(qw[0], true), a2 = __builtin_amdgcn_cvt_pk_f32_fp8(qw[1], false), a3 = __builtin_amdgcn_cvt_pk_f32_fp8(qw[1], true);
;       u32x4 pw; pw[0] = cvt_pk_bf16(a0[0], a0[1]); pw[1] = cvt_pk_bf16(a1[0], a1[1]); pw[2] = cvt_pk_bf16(a2[0], a2[1]); pw[3] = cvt_pk_bf16(a3[0], a3[1]);
;       union { u32x4 u; bf16x8 v; } cv; cv.u = pw; qB[s] = cv.v; }
;     epoch += 2u; pair_sync(pcnt, epoch, lane);
;     u32x4 stg[8];
;     const bf16_t* cbase = ckvn + (size_t)b * L * 256 + wch * 8;
;     ...
;     P4_LOAD(0);
;     P4_WRITE(cbuf + tok * CTOK);
;     if (nch > 1) P4_LOAD(1);
.LBB0_996:
	ds_read_b128 v[36:39], v167
	s_ashr_i32 s12, s21, 9
	s_ashr_i32 s13, s12, 31
	s_lshl_b64 s[12:13], s[12:13], 20
	v_lshl_add_u64 v[160:161], v[156:157], 0, s[12:13]
	s_waitcnt lgkmcnt(0)
	v_lshlrev_b32_e32 v0, 9, v36
	v_and_b32_e32 v0, 0x1fffe00, v0
	v_lshl_add_u64 v[2:3], v[160:161], 0, v[0:1]
	v_lshlrev_b32_sdwa v0, v171, v36 dst_sel:DWORD dst_unused:UNUSED_PAD src0_sel:DWORD src1_sel:WORD_1
	v_lshl_add_u64 v[40:41], v[160:161], 0, v[0:1]
	v_lshlrev_b32_e32 v0, 9, v37
	v_and_b32_e32 v0, 0x1fffe00, v0
	global_load_dwordx4 v[44:47], v[2:3], off
	global_load_dwordx4 v[48:51], v[40:41], off
	v_lshl_add_u64 v[2:3], v[160:161], 0, v[0:1]
	v_lshlrev_b32_sdwa v0, v171, v37 dst_sel:DWORD dst_unused:UNUSED_PAD src0_sel:DWORD src1_sel:WORD_1
	v_lshl_add_u64 v[36:37], v[160:161], 0, v[0:1]
	v_lshlrev_b32_e32 v0, 9, v38
	v_and_b32_e32 v0, 0x1fffe00, v0
	global_load_dwordx4 v[60:63], v[2:3], off
	global_load_dwordx4 v[68:71], v[36:37], off
	v_lshl_add_u64 v[2:3], v[160:161], 0, v[0:1]
	v_lshlrev_b32_sdwa v0, v171, v38 dst_sel:DWORD dst_unused:UNUSED_PAD src0_sel:DWORD src1_sel:WORD_1
	v_lshl_add_u64 v[36:37], v[160:161], 0, v[0:1]
	v_lshlrev_b32_e32 v0, 9, v39
	v_and_b32_e32 v0, 0x1fffe00, v0
	global_load_dwordx4 v[84:87], v[2:3], off
	global_load_dwordx4 v[88:91], v[36:37], off
	v_lshl_add_u64 v[2:3], v[160:161], 0, v[0:1]
	v_lshlrev_b32_sdwa v0, v171, v39 dst_sel:DWORD dst_unused:UNUSED_PAD src0_sel:DWORD src1_sel:WORD_1
	global_load_dwordx4 v[100:103], v[2:3], off
	v_lshl_add_u64 v[2:3], v[160:161], 0, v[0:1]
	global_load_dwordx4 v[108:111], v[2:3], off
	s_add_i32 s28, s20, 1
	s_mul_i32 s29, s28, s89
	s_mul_i32 s30, s28, 37
	s_add_i32 s30, s30, s88
	v_readlane_b32 s31, v254, 32
	s_mul_hi_u32 s31, s30, s31
	v_readlane_b32 s33, v254, 33
	s_mul_i32 s31, s31, s33
	s_sub_i32 s30, s30, s31
	s_sub_i32 s31, s30, s33
	s_cmp_ge_u32 s30, s33
	s_cselect_b32 s30, s31, s30
	s_sub_i32 s31, s30, s33
	s_cmp_ge_u32 s30, s33
	s_cselect_b32 s30, s31, s30
	s_add_i32 s30, s30, s29
	s_cmpk_gt_i32 s29, 0x1fff
	s_cselect_b32 s30, s21, s30
	s_lshl_b32 s30, s30, 11
	s_mov_b32 s31, 0
	v_lshl_add_u64 v[2:3], v[150:151], 0, s[30:31]
	global_load_dword v255, v[2:3], off
	s_waitcnt vmcnt(16)
	v_cvt_pk_f32_fp8_e32 v[202:203], v218
	v_cvt_pk_f32_fp8_sdwa v[204:205], v218 src0_sel:WORD_1
	v_cvt_pk_f32_fp8_e32 v[206:207], v219
	v_cvt_pk_f32_fp8_sdwa v[208:209], v219 src0_sel:WORD_1
	v_cvt_pk_bf16_f32 v4, v202, v203
	v_cvt_pk_bf16_f32 v5, v204, v205
	v_cvt_pk_bf16_f32 v6, v206, v207
	v_cvt_pk_bf16_f32 v7, v208, v209
	s_waitcnt vmcnt(15)
	v_cvt_pk_f32_fp8_e32 v[210:211], v220
	v_cvt_pk_f32_fp8_sdwa v[212:213], v220 src0_sel:WORD_1
	v_cvt_pk_f32_fp8_e32 v[214:215], v221
	v_cvt_pk_f32_fp8_sdwa v[216:217], v221 src0_sel:WORD_1
	v_cvt_pk_bf16_f32 v8, v210, v211
	v_cvt_pk_bf16_f32 v9, v212, v213
	v_cvt_pk_bf16_f32 v10, v214, v215
	v_cvt_pk_bf16_f32 v11, v216, v217
	s_waitcnt vmcnt(14)
	v_cvt_pk_f32_fp8_e32 v[202:203], v222
	v_cvt_pk_f32_fp8_sdwa v[204:205], v222 src0_sel:WORD_1
	v_cvt_pk_f32_fp8_e32 v[206:207], v223
	v_cvt_pk_f32_fp8_sdwa v[208:209], v223 src0_sel:WORD_1
	v_cvt_pk_bf16_f32 v12, v202, v203
	v_cvt_pk_bf16_f32 v13, v204, v205
	v_cvt_pk_bf16_f32 v14, v206, v207
	v_cvt_pk_bf16_f32 v15, v208, v209
	s_waitcnt vmcnt(13)
	v_cvt_pk_f32_fp8_e32 v[210:211], v224
	v_cvt_pk_f32_fp8_sdwa v[212:213], v224 src0_sel:WORD_1
	v_cvt_pk_f32_fp8_e32 v[214:215], v225
	v_cvt_pk_f32_fp8_sdwa v[216:217], v225 src0_sel:WORD_1
	v_cvt_pk_bf16_f32 v16, v210, v211
	v_cvt_pk_bf16_f32 v17, v212, v213
	v_cvt_pk_bf16_f32 v18, v214, v215
	v_cvt_pk_bf16_f32 v19, v216, v217
	s_waitcnt vmcnt(12)
	v_cvt_pk_f32_fp8_e32 v[202:203], v226
	v_cvt_pk_f32_fp8_sdwa v[204:205], v226 src0_sel:WORD_1
	v_cvt_pk_f32_fp8_e32 v[206:207], v227
	v_cvt_pk_f32_fp8_sdwa v[208:209], v227 src0_sel:WORD_1
	v_cvt_pk_bf16_f32 v20, v202, v203
	v_cvt_pk_bf16_f32 v21, v204, v205
	v_cvt_pk_bf16_f32 v22, v206, v207
	v_cvt_pk_bf16_f32 v23, v208, v209
	s_waitcnt vmcnt(11)
	v_cvt_pk_f32_fp8_e32 v[210:211], v228
	v_cvt_pk_f32_fp8_sdwa v[212:213], v228 src0_sel:WORD_1
	v_cvt_pk_f32_fp8_e32 v[214:215], v229
	v_cvt_pk_f32_fp8_sdwa v[216:217], v229 src0_sel:WORD_1
	v_cvt_pk_bf16_f32 v24, v210, v211
	v_cvt_pk_bf16_f32 v25, v212, v213
	v_cvt_pk_bf16_f32 v26, v214, v215
	v_cvt_pk_bf16_f32 v27, v216, v217
	s_waitcnt vmcnt(10)
	v_cvt_pk_f32_fp8_e32 v[202:203], v230
	v_cvt_pk_f32_fp8_sdwa v[204:205], v230 src0_sel:WORD_1
	v_cvt_pk_f32_fp8_e32 v[206:207], v231
	v_cvt_pk_f32_fp8_sdwa v[208:209], v231 src0_sel:WORD_1
	v_cvt_pk_bf16_f32 v28, v202, v203
	v_cvt_pk_bf16_f32 v29, v204, v205
	v_cvt_pk_bf16_f32 v30, v206, v207
	v_cvt_pk_bf16_f32 v31, v208, v209
	s_waitcnt vmcnt(9)
	v_cvt_pk_f32_fp8_e32 v[210:211], v232
	v_cvt_pk_f32_fp8_sdwa v[212:213], v232 src0_sel:WORD_1
	v_cvt_pk_f32_fp8_e32 v[214:215], v233
	v_cvt_pk_f32_fp8_sdwa v[216:217], v233 src0_sel:WORD_1
	v_cvt_pk_bf16_f32 v32, v210, v211
	v_cvt_pk_bf16_f32 v33, v212, v213
	v_cvt_pk_bf16_f32 v34, v214, v215
	v_cvt_pk_bf16_f32 v35, v216, v217
	s_and_b32 s14, s10, 0x7fc
	s_cmp_lt_u32 s14, 29
	s_waitcnt vmcnt(8)
	ds_write_b128 v170, v[44:47]
	s_waitcnt vmcnt(7)
	ds_write_b128 v170, v[48:51] offset:544
	s_waitcnt vmcnt(6)
	ds_write_b128 v170, v[60:63] offset:1088
	s_waitcnt vmcnt(5)
	ds_write_b128 v170, v[68:71] offset:1632
	s_waitcnt vmcnt(4)
	ds_write_b128 v170, v[84:87] offset:2176
	s_waitcnt vmcnt(3)
	ds_write_b128 v170, v[88:91] offset:2720
	s_waitcnt vmcnt(2)
	ds_write_b128 v170, v[100:103] offset:3264
	s_waitcnt vmcnt(1)
	ds_write_b128 v170, v[108:111] offset:3808
	s_cbranch_scc1 .LBB0_998
; #define P4_LOAD(ch) do { const u32x4 kk_ = *(const LAS u32x4*)(idxs + tok * 256 + (ch) * 32 + wrow); \
;       _Pragma("unroll") for (int i = 0; i < 8; ++i) { \
;       const int key = (int)((kk_[i >> 1] >> (16 * (i & 1))) & 0xffffu); stg[i] = *(const u32x4*)(cbase + (size_t)key * 256); } } while (0)
; #define P4_WRITE(bufp) do { _Pragma("unroll") for (int i = 0; i < 8; ++i) \
;       *(LAS u32x4*)((bufp) + (wrow + i) * CROW + 16 * (wch ^ (lane >> 5))) = stg[i]; } while (0)
; __device__ __forceinline__ void p4_attn(const Params& p, unsigned char* lds, int bid, int nb, bool dry) {
;     ...
;     P4_LOAD(0);
;     P4_WRITE(cbuf + tok * CTOK);
;     if (nch > 1) P4_LOAD(1);
;     ...
;       if (ch + 1 < nch) { P4_WRITE(cbuf + ((ch + 1) & 1) * CBUF + tok * CTOK); if (ch + 2 < nch) P4_LOAD(ch + 2); }
	ds_read_b128 v[36:39], v167 offset:64
	s_waitcnt lgkmcnt(0)
	v_lshlrev_b32_e32 v0, 9, v36
	v_and_b32_e32 v0, 0x1fffe00, v0
	v_lshl_add_u64 v[2:3], v[160:161], 0, v[0:1]
	v_lshlrev_b32_sdwa v0, v171, v36 dst_sel:DWORD dst_unused:UNUSED_PAD src0_sel:DWORD src1_sel:WORD_1
	v_lshl_add_u64 v[206:207], v[160:161], 0, v[0:1]
	global_load_dwordx4 v[202:205], v[2:3], off
	global_load_dwordx4 v[206:209], v[206:207], off
	v_lshlrev_b32_e32 v0, 9, v37
	v_and_b32_e32 v0, 0x1fffe00, v0
	v_lshl_add_u64 v[2:3], v[160:161], 0, v[0:1]
	v_lshlrev_b32_sdwa v0, v171, v37 dst_sel:DWORD dst_unused:UNUSED_PAD src0_sel:DWORD src1_sel:WORD_1
	v_lshl_add_u64 v[214:215], v[160:161], 0, v[0:1]
	global_load_dwordx4 v[210:213], v[2:3], off
	global_load_dwordx4 v[214:217], v[214:215], off
	v_lshlrev_b32_e32 v0, 9, v38
	v_and_b32_e32 v0, 0x1fffe00, v0
	v_lshl_add_u64 v[2:3], v[160:161], 0, v[0:1]
	v_lshlrev_b32_sdwa v0, v171, v38 dst_sel:DWORD dst_unused:UNUSED_PAD src0_sel:DWORD src1_sel:WORD_1
	v_lshl_add_u64 v[222:223], v[160:161], 0, v[0:1]
	global_load_dwordx4 v[218:221], v[2:3], off
	global_load_dwordx4 v[222:225], v[222:223], off
	v_lshlrev_b32_e32 v0, 9, v39
	v_and_b32_e32 v0, 0x1fffe00, v0
	v_lshl_add_u64 v[2:3], v[160:161], 0, v[0:1]
	v_lshlrev_b32_sdwa v0, v171, v39 dst_sel:DWORD dst_unused:UNUSED_PAD src0_sel:DWORD src1_sel:WORD_1
	v_lshl_add_u64 v[230:231], v[160:161], 0, v[0:1]
	global_load_dwordx4 v[226:229], v[2:3], off
	global_load_dwordx4 v[230:233], v[230:231], off
	s_cmp_lt_u32 s14, 61
	s_cbranch_scc1 .LBB0_998
	ds_read_b128 v[36:39], v167 offset:128
	s_waitcnt lgkmcnt(0)
	v_lshlrev_b32_e32 v0, 9, v36
	v_and_b32_e32 v0, 0x1fffe00, v0
	v_lshl_add_u64 v[2:3], v[160:161], 0, v[0:1]
	v_lshlrev_b32_sdwa v0, v171, v36 dst_sel:DWORD dst_unused:UNUSED_PAD src0_sel:DWORD src1_sel:WORD_1
	v_lshl_add_u64 v[48:49], v[160:161], 0, v[0:1]
	global_load_dwordx4 v[44:47], v[2:3], off
	global_load_dwordx4 v[48:51], v[48:49], off
	v_lshlrev_b32_e32 v0, 9, v37
	v_and_b32_e32 v0, 0x1fffe00, v0
	v_lshl_add_u64 v[2:3], v[160:161], 0, v[0:1]
	v_lshlrev_b32_sdwa v0, v171, v37 dst_sel:DWORD dst_unused:UNUSED_PAD src0_sel:DWORD src1_sel:WORD_1
	v_lshl_add_u64 v[68:69], v[160:161], 0, v[0:1]
	global_load_dwordx4 v[60:63], v[2:3], off
	global_load_dwordx4 v[68:71], v[68:69], off
	v_lshlrev_b32_e32 v0, 9, v38
	v_and_b32_e32 v0, 0x1fffe00, v0
	v_lshl_add_u64 v[2:3], v[160:161], 0, v[0:1]
	v_lshlrev_b32_sdwa v0, v171, v38 dst_sel:DWORD dst_unused:UNUSED_PAD src0_sel:DWORD src1_sel:WORD_1
	v_lshl_add_u64 v[88:89], v[160:161], 0, v[0:1]
	global_load_dwordx4 v[84:87], v[2:3], off
	global_load_dwordx4 v[88:91], v[88:89], off
	v_lshlrev_b32_e32 v0, 9, v39
	v_and_b32_e32 v0, 0x1fffe00, v0
	v_lshl_add_u64 v[2:3], v[160:161], 0, v[0:1]
	v_lshlrev_b32_sdwa v0, v171, v39 dst_sel:DWORD dst_unused:UNUSED_PAD src0_sel:DWORD src1_sel:WORD_1
	v_lshl_add_u64 v[108:109], v[160:161], 0, v[0:1]
	global_load_dwordx4 v[100:103], v[2:3], off
	global_load_dwordx4 v[108:111], v[108:109], off

; #define LAS __attribute__((address_space(3)))
; #define P4_LOAD(ch) do { const u32x4 kk_ = *(const LAS u32x4*)(idxs + tok * 256 + (ch) * 32 + wrow); \
;       _Pragma("unroll") for (int i = 0; i < 8; ++i) { \
;       const int key = (int)((kk_[i >> 1] >> (16 * (i & 1))) & 0xffffu); stg[i] = *(const u32x4*)(cbase + (size_t)key * 256); } } while (0)
; #define P4_WRITE(bufp) do { _Pragma("unroll") for (int i = 0; i < 8; ++i) \
;       *(LAS u32x4*)((bufp) + (wrow + i) * CROW + 16 * (wch ^ (lane >> 5))) = stg[i]; } while (0)
; __device__ __forceinline__ void p4_attn(const Params& p, unsigned char* lds, int bid, int nb, bool dry) {
;     ...
;     for (int ch = 0; ch < nch; ++ch) {
;       LAS unsigned char* cb = cbuf + (ch & 1) * CBUF + tok * CTOK;
;       if (ch + 1 < nch) { P4_WRITE(cbuf + ((ch + 1) & 1) * CBUF + tok * CTOK); if (ch + 2 < nch) P4_LOAD(ch + 2); }
;       f32x4 s0 = (f32x4){0.f, 0.f, 0.f, 0.f}, s1 = (f32x4){0.f, 0.f, 0.f, 0.f};
; #pragma unroll
;       for (int s = 0; s < 8; ++s) {
;         const bf16x8 a0 = *(const LAS bf16x8*)(cb + r16 * CROW + s * 64 + qoff);
;         const bf16x8 a1 = *(const LAS bf16x8*)(cb + (16 + r16) * CROW + s * 64 + qoff);
;         s0 = __builtin_amdgcn_mfma_f32_16x16x32_bf16(a0, qB[s], s0, 0, 0, 0);
;         s1 = __builtin_amdgcn_mfma_f32_16x16x32_bf16(a1, qB[s], s1, 0, 0, 0);
;       }
.LBB0_1005:
	s_add_i32 s27, s10, 2
	s_cmp_ge_u32 s27, s21
	s_cbranch_scc1 .Lp4_w1
	s_bitcmp1_b32 s10, 0
	s_cbranch_scc1 .Lp4_w2_odd
	s_bitcmp1_b32 s10, 0
	s_cselect_b32 s11, 0x11000, 0
	s_add_i32 s12, s5, s11
	s_lshl_b32 s13, s10, 5
	v_add3_u32 v2, s12, v168, v162
	s_add_i32 s27, s10, 3
	v_lshl_add_u32 v3, s27, 6, v167
	ds_read_b128 v[196:199], v3
	ds_read_b128 v[234:237], v2
	ds_read_b128 v[238:241], v2 offset:8704
	ds_read_b128 v[242:245], v2 offset:64
	ds_read_b128 v[246:249], v2 offset:8768
	ds_read_b128 v[250:253], v2 offset:128
	ds_read_b128 v[188:191], v2 offset:8832
	v_or_b32_e32 v0, s13, v148
	v_lshl_add_u32 v3, v0, 1, s3
	s_bitcmp1_b32 s23, 0
	s_cselect_b32 s11, 0x11000, 0
	v_add_u32_e32 v201, s11, v170
	s_waitcnt lgkmcnt(5)
	v_mfma_f32_16x16x32_bf16 v[140:143], v[234:237], v[4:7], 0
	ds_read_b128 v[234:237], v2 offset:192
	s_waitcnt lgkmcnt(5)
	v_mfma_f32_16x16x32_bf16 v[144:147], v[238:241], v[4:7], 0
	ds_read_b128 v[238:241], v2 offset:8896
	ds_read2_b64 v[184:187], v3 offset1:4
	s_waitcnt lgkmcnt(6)
	v_mfma_f32_16x16x32_bf16 v[140:143], v[242:245], v[8:11], v[140:143]
	ds_read_b128 v[242:245], v2 offset:256
	s_waitcnt vmcnt(15)
	ds_write_b128 v201, v[202:205]
	s_waitcnt lgkmcnt(7)
	v_mfma_f32_16x16x32_bf16 v[144:147], v[246:249], v[8:11], v[144:147]
	ds_read_b128 v[246:249], v2 offset:8960
	s_waitcnt vmcnt(14)
	ds_write_b128 v201, v[206:209] offset:544
	s_waitcnt lgkmcnt(8)
	v_mfma_f32_16x16x32_bf16 v[140:143], v[250:253], v[12:15], v[140:143]
	ds_read_b128 v[250:253], v2 offset:320
	s_waitcnt vmcnt(13)
	ds_write_b128 v201, v[210:213] offset:1088
	s_waitcnt lgkmcnt(9)
	v_mfma_f32_16x16x32_bf16 v[144:147], v[188:191], v[12:15], v[144:147]
	ds_read_b128 v[188:191], v2 offset:9024
	s_waitcnt vmcnt(12)
	ds_write_b128 v201, v[214:217] offset:1632
	s_waitcnt lgkmcnt(10)
	v_mfma_f32_16x16x32_bf16 v[140:143], v[234:237], v[16:19], v[140:143]
	ds_read_b128 v[234:237], v2 offset:384
	s_waitcnt vmcnt(11)
	ds_write_b128 v201, v[218:221] offset:2176
	s_waitcnt lgkmcnt(11)
	v_mfma_f32_16x16x32_bf16 v[144:147], v[238:241], v[16:19], v[144:147]
	ds_read_b128 v[238:241], v2 offset:9088
	s_waitcnt vmcnt(10)
	ds_write_b128 v201, v[222:225] offset:2720
	s_waitcnt lgkmcnt(11)
	v_mfma_f32_16x16x32_bf16 v[140:143], v[242:245], v[20:23], v[140:143]
	ds_read_b128 v[242:245], v2 offset:448
	s_waitcnt vmcnt(9)
	ds_write_b128 v201, v[226:229] offset:3264
	s_waitcnt lgkmcnt(11)
	v_mfma_f32_16x16x32_bf16 v[144:147], v[246:249], v[20:23], v[144:147]
	ds_read_b128 v[246:249], v2 offset:9152
	s_waitcnt vmcnt(8)
	ds_write_b128 v201, v[230:233] offset:3808
	s_waitcnt lgkmcnt(11)
	v_mfma_f32_16x16x32_bf16 v[140:143], v[250:253], v[24:27], v[140:143]
	s_waitcnt lgkmcnt(9)
	v_mfma_f32_16x16x32_bf16 v[144:147], v[188:191], v[24:27], v[144:147]
	s_waitcnt lgkmcnt(7)
	v_mfma_f32_16x16x32_bf16 v[140:143], v[234:237], v[28:31], v[140:143]
	s_waitcnt lgkmcnt(5)
	v_mfma_f32_16x16x32_bf16 v[144:147], v[238:241], v[28:31], v[144:147]
	s_waitcnt lgkmcnt(3)
	v_mfma_f32_16x16x32_bf16 v[140:143], v[242:245], v[32:35], v[140:143]
	s_waitcnt lgkmcnt(1)
	v_mfma_f32_16x16x32_bf16 v[144:147], v[246:249], v[32:35], v[144:147]
	s_add_i32 s27, s10, 3
	s_cmp_ge_u32 s27, s21
	s_cbranch_scc1 .Lp4_softmax
	s_waitcnt lgkmcnt(0)
	v_lshlrev_b32_e32 v0, 9, v196
	v_and_b32_e32 v0, 0x1fffe00, v0
	v_lshl_add_u64 v[2:3], v[160:161], 0, v[0:1]
	v_lshlrev_b32_sdwa v0, v171, v196 dst_sel:DWORD dst_unused:UNUSED_PAD src0_sel:DWORD src1_sel:WORD_1
	v_lshl_add_u64 v[206:207], v[160:161], 0, v[0:1]
	global_load_dwordx4 v[202:205], v[2:3], off
	global_load_dwordx4 v[206:209], v[206:207], off
	v_lshlrev_b32_e32 v0, 9, v197
	v_and_b32_e32 v0, 0x1fffe00, v0
	v_lshl_add_u64 v[2:3], v[160:161], 0, v[0:1]
	v_lshlrev_b32_sdwa v0, v171, v197 dst_sel:DWORD dst_unused:UNUSED_PAD src0_sel:DWORD src1_sel:WORD_1
	v_lshl_add_u64 v[214:215], v[160:161], 0, v[0:1]
	global_load_dwordx4 v[210:213], v[2:3], off
	global_load_dwordx4 v[214:217], v[214:215], off
	v_lshlrev_b32_e32 v0, 9, v198
	v_and_b32_e32 v0, 0x1fffe00, v0
	v_lshl_add_u64 v[2:3], v[160:161], 0, v[0:1]
	v_lshlrev_b32_sdwa v0, v171, v198 dst_sel:DWORD dst_unused:UNUSED_PAD src0_sel:DWORD src1_sel:WORD_1
	v_lshl_add_u64 v[222:223], v[160:161], 0, v[0:1]
	global_load_dwordx4 v[218:221], v[2:3], off
	global_load_dwordx4 v[222:225], v[222:223], off
	v_lshlrev_b32_e32 v0, 9, v199
	v_and_b32_e32 v0, 0x1fffe00, v0
	v_lshl_add_u64 v[2:3], v[160:161], 0, v[0:1]
	v_lshlrev_b32_sdwa v0, v171, v199 dst_sel:DWORD dst_unused:UNUSED_PAD src0_sel:DWORD src1_sel:WORD_1
	v_lshl_add_u64 v[230:231], v[160:161], 0, v[0:1]
	global_load_dwordx4 v[226:229], v[2:3], off
	global_load_dwordx4 v[230:233], v[230:231], off
	s_branch .Lp4_softmax
; #define LAS __attribute__((address_space(3)))
; #define P4_LOAD(ch) do { const u32x4 kk_ = *(const LAS u32x4*)(idxs + tok * 256 + (ch) * 32 + wrow); \
;       _Pragma("unroll") for (int i = 0; i < 8; ++i) { \
;       const int key = (int)((kk_[i >> 1] >> (16 * (i & 1))) & 0xffffu); stg[i] = *(const u32x4*)(cbase + (size_t)key * 256); } } while (0)
; #define P4_WRITE(bufp) do { _Pragma("unroll") for (int i = 0; i < 8; ++i) \
;       *(LAS u32x4*)((bufp) + (wrow + i) * CROW + 16 * (wch ^ (lane >> 5))) = stg[i]; } while (0)
; __device__ __forceinline__ void p4_attn(const Params& p, unsigned char* lds, int bid, int nb, bool dry) {
;     ...
;     for (int ch = 0; ch < nch; ++ch) {
;       LAS unsigned char* cb = cbuf + (ch & 1) * CBUF + tok * CTOK;
;       if (ch + 1 < nch) { P4_WRITE(cbuf + ((ch + 1) & 1) * CBUF + tok * CTOK); if (ch + 2 < nch) P4_LOAD(ch + 2); }
;       f32x4 s0 = (f32x4){0.f, 0.f, 0.f, 0.f}, s1 = (f32x4){0.f, 0.f, 0.f, 0.f};
; #pragma unroll
;       for (int s = 0; s < 8; ++s) {
;         const bf16x8 a0 = *(const LAS bf16x8*)(cb + r16 * CROW + s * 64 + qoff);
;         const bf16x8 a1 = *(const LAS bf16x8*)(cb + (16 + r16) * CROW + s * 64 + qoff);
;         s0 = __builtin_amdgcn_mfma_f32_16x16x32_bf16(a0, qB[s], s0, 0, 0, 0);
;         s1 = __builtin_amdgcn_mfma_f32_16x16x32_bf16(a1, qB[s], s1, 0, 0, 0);
;       }
.Lp4_w2_odd:
	s_bitcmp1_b32 s10, 0
	s_cselect_b32 s11, 0x11000, 0
	s_add_i32 s12, s5, s11
	s_lshl_b32 s13, s10, 5
	v_add3_u32 v2, s12, v168, v162
	s_add_i32 s27, s10, 3
	v_lshl_add_u32 v3, s27, 6, v167
	ds_read_b128 v[196:199], v3
	ds_read_b128 v[234:237], v2
	ds_read_b128 v[238:241], v2 offset:8704
	ds_read_b128 v[242:245], v2 offset:64
	ds_read_b128 v[246:249], v2 offset:8768
	ds_read_b128 v[250:253], v2 offset:128
	ds_read_b128 v[188:191], v2 offset:8832
	v_or_b32_e32 v0, s13, v148
	v_lshl_add_u32 v3, v0, 1, s3
	s_bitcmp1_b32 s23, 0
	s_cselect_b32 s11, 0x11000, 0
	v_add_u32_e32 v201, s11, v170
	s_waitcnt lgkmcnt(5)
	v_mfma_f32_16x16x32_bf16 v[140:143], v[234:237], v[4:7], 0
	ds_read_b128 v[234:237], v2 offset:192
	s_waitcnt lgkmcnt(5)
	v_mfma_f32_16x16x32_bf16 v[144:147], v[238:241], v[4:7], 0
	ds_read_b128 v[238:241], v2 offset:8896
	ds_read2_b64 v[184:187], v3 offset1:4
	s_waitcnt lgkmcnt(6)
	v_mfma_f32_16x16x32_bf16 v[140:143], v[242:245], v[8:11], v[140:143]
	ds_read_b128 v[242:245], v2 offset:256
	s_waitcnt vmcnt(15)
	ds_write_b128 v201, v[44:47]
	s_waitcnt lgkmcnt(7)
	v_mfma_f32_16x16x32_bf16 v[144:147], v[246:249], v[8:11], v[144:147]
	ds_read_b128 v[246:249], v2 offset:8960
	s_waitcnt vmcnt(14)
	ds_write_b128 v201, v[48:51] offset:544
	s_waitcnt lgkmcnt(8)
	v_mfma_f32_16x16x32_bf16 v[140:143], v[250:253], v[12:15], v[140:143]
	ds_read_b128 v[250:253], v2 offset:320
	s_waitcnt vmcnt(13)
	ds_write_b128 v201, v[60:63] offset:1088
	s_waitcnt lgkmcnt(9)
	v_mfma_f32_16x16x32_bf16 v[144:147], v[188:191], v[12:15], v[144:147]
	ds_read_b128 v[188:191], v2 offset:9024
	s_waitcnt vmcnt(12)
	ds_write_b128 v201, v[68:71] offset:1632
	s_waitcnt lgkmcnt(10)
	v_mfma_f32_16x16x32_bf16 v[140:143], v[234:237], v[16:19], v[140:143]
	ds_read_b128 v[234:237], v2 offset:384
	s_waitcnt vmcnt(11)
	ds_write_b128 v201, v[84:87] offset:2176
	s_waitcnt lgkmcnt(11)
	v_mfma_f32_16x16x32_bf16 v[144:147], v[238:241], v[16:19], v[144:147]
	ds_read_b128 v[238:241], v2 offset:9088
	s_waitcnt vmcnt(10)
	ds_write_b128 v201, v[88:91] offset:2720
	s_waitcnt lgkmcnt(11)
	v_mfma_f32_16x16x32_bf16 v[140:143], v[242:245], v[20:23], v[140:143]
	ds_read_b128 v[242:245], v2 offset:448
	s_waitcnt vmcnt(9)
	ds_write_b128 v201, v[100:103] offset:3264
	s_waitcnt lgkmcnt(11)
	v_mfma_f32_16x16x32_bf16 v[144:147], v[246:249], v[20:23], v[144:147]
	ds_read_b128 v[246:249], v2 offset:9152
	s_waitcnt vmcnt(8)
	ds_write_b128 v201, v[108:111] offset:3808
	s_waitcnt lgkmcnt(11)
	v_mfma_f32_16x16x32_bf16 v[140:143], v[250:253], v[24:27], v[140:143]
	s_waitcnt lgkmcnt(9)
	v_mfma_f32_16x16x32_bf16 v[144:147], v[188:191], v[24:27], v[144:147]
	s_waitcnt lgkmcnt(7)
	v_mfma_f32_16x16x32_bf16 v[140:143], v[234:237], v[28:31], v[140:143]
	s_waitcnt lgkmcnt(5)
	v_mfma_f32_16x16x32_bf16 v[144:147], v[238:241], v[28:31], v[144:147]
	s_waitcnt lgkmcnt(3)
	v_mfma_f32_16x16x32_bf16 v[140:143], v[242:245], v[32:35], v[140:143]
	s_waitcnt lgkmcnt(1)
	v_mfma_f32_16x16x32_bf16 v[144:147], v[246:249], v[32:35], v[144:147]
	s_add_i32 s27, s10, 3
	s_cmp_ge_u32 s27, s21
	s_cbranch_scc1 .Lp4_softmax
	s_waitcnt lgkmcnt(0)
	v_lshlrev_b32_e32 v0, 9, v196
	v_and_b32_e32 v0, 0x1fffe00, v0
	v_lshl_add_u64 v[2:3], v[160:161], 0, v[0:1]
	v_lshlrev_b32_sdwa v0, v171, v196 dst_sel:DWORD dst_unused:UNUSED_PAD src0_sel:DWORD src1_sel:WORD_1
	v_lshl_add_u64 v[48:49], v[160:161], 0, v[0:1]
	global_load_dwordx4 v[44:47], v[2:3], off
	global_load_dwordx4 v[48:51], v[48:49], off
	v_lshlrev_b32_e32 v0, 9, v197
	v_and_b32_e32 v0, 0x1fffe00, v0
	v_lshl_add_u64 v[2:3], v[160:161], 0, v[0:1]
	v_lshlrev_b32_sdwa v0, v171, v197 dst_sel:DWORD dst_unused:UNUSED_PAD src0_sel:DWORD src1_sel:WORD_1
	v_lshl_add_u64 v[68:69], v[160:161], 0, v[0:1]
	global_load_dwordx4 v[60:63], v[2:3], off
	global_load_dwordx4 v[68:71], v[68:69], off
	v_lshlrev_b32_e32 v0, 9, v198
	v_and_b32_e32 v0, 0x1fffe00, v0
	v_lshl_add_u64 v[2:3], v[160:161], 0, v[0:1]
	v_lshlrev_b32_sdwa v0, v171, v198 dst_sel:DWORD dst_unused:UNUSED_PAD src0_sel:DWORD src1_sel:WORD_1
	v_lshl_add_u64 v[88:89], v[160:161], 0, v[0:1]
	global_load_dwordx4 v[84:87], v[2:3], off
	global_load_dwordx4 v[88:91], v[88:89], off
	v_lshlrev_b32_e32 v0, 9, v199
	v_and_b32_e32 v0, 0x1fffe00, v0
	v_lshl_add_u64 v[2:3], v[160:161], 0, v[0:1]
	v_lshlrev_b32_sdwa v0, v171, v199 dst_sel:DWORD dst_unused:UNUSED_PAD src0_sel:DWORD src1_sel:WORD_1
	v_lshl_add_u64 v[108:109], v[160:161], 0, v[0:1]
	global_load_dwordx4 v[100:103], v[2:3], off
	global_load_dwordx4 v[108:111], v[108:109], off
	s_branch .Lp4_softmax
; #define LAS __attribute__((address_space(3)))
; #define P4_LOAD(ch) do { const u32x4 kk_ = *(const LAS u32x4*)(idxs + tok * 256 + (ch) * 32 + wrow); \
;       _Pragma("unroll") for (int i = 0; i < 8; ++i) { \
;       const int key = (int)((kk_[i >> 1] >> (16 * (i & 1))) & 0xffffu); stg[i] = *(const u32x4*)(cbase + (size_t)key * 256); } } while (0)
; #define P4_WRITE(bufp) do { _Pragma("unroll") for (int i = 0; i < 8; ++i) \
;       *(LAS u32x4*)((bufp) + (wrow + i) * CROW + 16 * (wch ^ (lane >> 5))) = stg[i]; } while (0)
; __device__ __forceinline__ void p4_attn(const Params& p, unsigned char* lds, int bid, int nb, bool dry) {
;     ...
;     for (int ch = 0; ch < nch; ++ch) {
;       LAS unsigned char* cb = cbuf + (ch & 1) * CBUF + tok * CTOK;
;       if (ch + 1 < nch) { P4_WRITE(cbuf + ((ch + 1) & 1) * CBUF + tok * CTOK); if (ch + 2 < nch) P4_LOAD(ch + 2); }
;       f32x4 s0 = (f32x4){0.f, 0.f, 0.f, 0.f}, s1 = (f32x4){0.f, 0.f, 0.f, 0.f};
; #pragma unroll
;       for (int s = 0; s < 8; ++s) {
;         const bf16x8 a0 = *(const LAS bf16x8*)(cb + r16 * CROW + s * 64 + qoff);
;         const bf16x8 a1 = *(const LAS bf16x8*)(cb + (16 + r16) * CROW + s * 64 + qoff);
;         s0 = __builtin_amdgcn_mfma_f32_16x16x32_bf16(a0, qB[s], s0, 0, 0, 0);
;         s1 = __builtin_amdgcn_mfma_f32_16x16x32_bf16(a1, qB[s], s1, 0, 0, 0);
;       }
.Lp4_w1:
	s_bitcmp1_b32 s10, 0
	s_cbranch_scc1 .Lp4_w1_odd
	s_bitcmp1_b32 s10, 0
	s_cselect_b32 s11, 0x11000, 0
	s_add_i32 s12, s5, s11
	s_lshl_b32 s13, s10, 5
	v_add3_u32 v2, s12, v168, v162
	ds_read_b128 v[234:237], v2
	ds_read_b128 v[238:241], v2 offset:8704
	ds_read_b128 v[242:245], v2 offset:64
	ds_read_b128 v[246:249], v2 offset:8768
	ds_read_b128 v[250:253], v2 offset:128
	ds_read_b128 v[188:191], v2 offset:8832
	v_or_b32_e32 v0, s13, v148
	v_lshl_add_u32 v3, v0, 1, s3
	s_bitcmp1_b32 s23, 0
	s_cselect_b32 s11, 0x11000, 0
	v_add_u32_e32 v201, s11, v170
	s_waitcnt lgkmcnt(5)
	v_mfma_f32_16x16x32_bf16 v[140:143], v[234:237], v[4:7], 0
	ds_read_b128 v[234:237], v2 offset:192
	s_waitcnt lgkmcnt(5)
	v_mfma_f32_16x16x32_bf16 v[144:147], v[238:241], v[4:7], 0
	ds_read_b128 v[238:241], v2 offset:8896
	ds_read2_b64 v[184:187], v3 offset1:4
	s_waitcnt lgkmcnt(6)
	v_mfma_f32_16x16x32_bf16 v[140:143], v[242:245], v[8:11], v[140:143]
	ds_read_b128 v[242:245], v2 offset:256
	s_waitcnt vmcnt(7)
	ds_write_b128 v201, v[202:205]
	s_waitcnt lgkmcnt(7)
	v_mfma_f32_16x16x32_bf16 v[144:147], v[246:249], v[8:11], v[144:147]
	ds_read_b128 v[246:249], v2 offset:8960
	s_waitcnt vmcnt(6)
	ds_write_b128 v201, v[206:209] offset:544
	s_waitcnt lgkmcnt(8)
	v_mfma_f32_16x16x32_bf16 v[140:143], v[250:253], v[12:15], v[140:143]
	ds_read_b128 v[250:253], v2 offset:320
	s_waitcnt vmcnt(5)
	ds_write_b128 v201, v[210:213] offset:1088
	s_waitcnt lgkmcnt(9)
	v_mfma_f32_16x16x32_bf16 v[144:147], v[188:191], v[12:15], v[144:147]
	ds_read_b128 v[188:191], v2 offset:9024
	s_waitcnt vmcnt(4)
	ds_write_b128 v201, v[214:217] offset:1632
	s_waitcnt lgkmcnt(10)
	v_mfma_f32_16x16x32_bf16 v[140:143], v[234:237], v[16:19], v[140:143]
	ds_read_b128 v[234:237], v2 offset:384
	s_waitcnt vmcnt(3)
	ds_write_b128 v201, v[218:221] offset:2176
	s_waitcnt lgkmcnt(11)
	v_mfma_f32_16x16x32_bf16 v[144:147], v[238:241], v[16:19], v[144:147]
	ds_read_b128 v[238:241], v2 offset:9088
	s_waitcnt vmcnt(2)
	ds_write_b128 v201, v[222:225] offset:2720
	s_waitcnt lgkmcnt(11)
	v_mfma_f32_16x16x32_bf16 v[140:143], v[242:245], v[20:23], v[140:143]
	ds_read_b128 v[242:245], v2 offset:448
	s_waitcnt vmcnt(1)
	ds_write_b128 v201, v[226:229] offset:3264
	s_waitcnt lgkmcnt(11)
	v_mfma_f32_16x16x32_bf16 v[144:147], v[246:249], v[20:23], v[144:147]
	ds_read_b128 v[246:249], v2 offset:9152
	s_waitcnt vmcnt(0)
	ds_write_b128 v201, v[230:233] offset:3808
	s_waitcnt lgkmcnt(11)
	v_mfma_f32_16x16x32_bf16 v[140:143], v[250:253], v[24:27], v[140:143]
	s_waitcnt lgkmcnt(9)
	v_mfma_f32_16x16x32_bf16 v[144:147], v[188:191], v[24:27], v[144:147]
	s_waitcnt lgkmcnt(7)
	v_mfma_f32_16x16x32_bf16 v[140:143], v[234:237], v[28:31], v[140:143]
	s_waitcnt lgkmcnt(5)
	v_mfma_f32_16x16x32_bf16 v[144:147], v[238:241], v[28:31], v[144:147]
	s_waitcnt lgkmcnt(3)
	v_mfma_f32_16x16x32_bf16 v[140:143], v[242:245], v[32:35], v[140:143]
	s_waitcnt lgkmcnt(1)
	v_mfma_f32_16x16x32_bf16 v[144:147], v[246:249], v[32:35], v[144:147]
	s_branch .Lp4_softmax
.Lp4_w1_odd:
	s_bitcmp1_b32 s10, 0
	s_cselect_b32 s11, 0x11000, 0
	s_add_i32 s12, s5, s11
	s_lshl_b32 s13, s10, 5
	v_add3_u32 v2, s12, v168, v162
	ds_read_b128 v[234:237], v2
	ds_read_b128 v[238:241], v2 offset:8704
	ds_read_b128 v[242:245], v2 offset:64
	ds_read_b128 v[246:249], v2 offset:8768
	ds_read_b128 v[250:253], v2 offset:128
	ds_read_b128 v[188:191], v2 offset:8832
	v_or_b32_e32 v0, s13, v148
	v_lshl_add_u32 v3, v0, 1, s3
	s_bitcmp1_b32 s23, 0
	s_cselect_b32 s11, 0x11000, 0
	v_add_u32_e32 v201, s11, v170
	s_waitcnt lgkmcnt(5)
	v_mfma_f32_16x16x32_bf16 v[140:143], v[234:237], v[4:7], 0
	ds_read_b128 v[234:237], v2 offset:192
	s_waitcnt lgkmcnt(5)
	v_mfma_f32_16x16x32_bf16 v[144:147], v[238:241], v[4:7], 0
	ds_read_b128 v[238:241], v2 offset:8896
	ds_read2_b64 v[184:187], v3 offset1:4
	s_waitcnt lgkmcnt(6)
	v_mfma_f32_16x16x32_bf16 v[140:143], v[242:245], v[8:11], v[140:143]
	ds_read_b128 v[242:245], v2 offset:256
	s_waitcnt vmcnt(7)
	ds_write_b128 v201, v[44:47]
	s_waitcnt lgkmcnt(7)
	v_mfma_f32_16x16x32_bf16 v[144:147], v[246:249], v[8:11], v[144:147]
	ds_read_b128 v[246:249], v2 offset:8960
	s_waitcnt vmcnt(6)
	ds_write_b128 v201, v[48:51] offset:544
	s_waitcnt lgkmcnt(8)
	v_mfma_f32_16x16x32_bf16 v[140:143], v[250:253], v[12:15], v[140:143]
	ds_read_b128 v[250:253], v2 offset:320
	s_waitcnt vmcnt(5)
	ds_write_b128 v201, v[60:63] offset:1088
	s_waitcnt lgkmcnt(9)
	v_mfma_f32_16x16x32_bf16 v[144:147], v[188:191], v[12:15], v[144:147]
	ds_read_b128 v[188:191], v2 offset:9024
	s_waitcnt vmcnt(4)
	ds_write_b128 v201, v[68:71] offset:1632
	s_waitcnt lgkmcnt(10)
	v_mfma_f32_16x16x32_bf16 v[140:143], v[234:237], v[16:19], v[140:143]
	ds_read_b128 v[234:237], v2 offset:384
	s_waitcnt vmcnt(3)
	ds_write_b128 v201, v[84:87] offset:2176
	s_waitcnt lgkmcnt(11)
	v_mfma_f32_16x16x32_bf16 v[144:147], v[238:241], v[16:19], v[144:147]
	ds_read_b128 v[238:241], v2 offset:9088
	s_waitcnt vmcnt(2)
	ds_write_b128 v201, v[88:91] offset:2720
	s_waitcnt lgkmcnt(11)
	v_mfma_f32_16x16x32_bf16 v[140:143], v[242:245], v[20:23], v[140:143]
	ds_read_b128 v[242:245], v2 offset:448
	s_waitcnt vmcnt(1)
	ds_write_b128 v201, v[100:103] offset:3264
	s_waitcnt lgkmcnt(11)
	v_mfma_f32_16x16x32_bf16 v[144:147], v[246:249], v[20:23], v[144:147]
	ds_read_b128 v[246:249], v2 offset:9152
	s_waitcnt vmcnt(0)
	ds_write_b128 v201, v[108:111] offset:3808
	s_waitcnt lgkmcnt(11)
	v_mfma_f32_16x16x32_bf16 v[140:143], v[250:253], v[24:27], v[140:143]
	s_waitcnt lgkmcnt(9)
	v_mfma_f32_16x16x32_bf16 v[144:147], v[188:191], v[24:27], v[144:147]
	s_waitcnt lgkmcnt(7)
	v_mfma_f32_16x16x32_bf16 v[140:143], v[234:237], v[28:31], v[140:143]
	s_waitcnt lgkmcnt(5)
	v_mfma_f32_16x16x32_bf16 v[144:147], v[238:241], v[28:31], v[144:147]
	s_waitcnt lgkmcnt(3)
	v_mfma_f32_16x16x32_bf16 v[140:143], v[242:245], v[32:35], v[140:143]
	s_waitcnt lgkmcnt(1)
	v_mfma_f32_16x16x32_bf16 v[144:147], v[246:249], v[32:35], v[144:147]
	s_branch .Lp4_softmax
; #define LAS __attribute__((address_space(3)))
; __device__ __forceinline__ void p4_attn(const Params& p, unsigned char* lds, int bid, int nb, bool dry) {
;     ...
;         const bf16x8 a0 = *(const LAS bf16x8*)(cb + r16 * CROW + s * 64 + qoff);
;         const bf16x8 a1 = *(const LAS bf16x8*)(cb + (16 + r16) * CROW + s * 64 + qoff);
;         s0 = __builtin_amdgcn_mfma_f32_16x16x32_bf16(a0, qB[s], s0, 0, 0, 0);
;         s1 = __builtin_amdgcn_mfma_f32_16x16x32_bf16(a1, qB[s], s1, 0, 0, 0);
;       }
;       const int slotb = ch * 32 + 4 * g;
;       const u32x2 k0 = *(const LAS u32x2*)(idxs + tok * 256 + slotb), k1 = *(const LAS u32x2*)(idxs + tok * 256 + slotb + 16);
;       float lg0[4], lg1[4]; float mx = -1e30f;
;       const bool full = (ch * 32 + 32 <= nk);
;       int dd0[4], dd1[4]; int dmin = 1 << 20;
; #pragma unroll
;       for (int i = 0; i < 4; ++i) {
;         const int key0 = (int)((k0[i >> 1] >> (16 * (i & 1))) & 0xffffu), key1 = (int)((k1[i >> 1] >> (16 * (i & 1))) & 0xffffu);
;         dd0[i] = t - key0; dd1[i] = t - key1; dmin = min(dmin, min(dd0[i], dd1[i]));
;       }
;       if (__ballot(dmin < 128) == 0ull) {
;         const float bfar = biasd[128 * 32 + head];
; #pragma unroll
;         for (int i = 0; i < 4; ++i) { lg0[i] = s0[i] * SC + bfar; lg1[i] = s1[i] * SC + bfar; }
;       } else {
; #pragma unroll
;         for (int i = 0; i < 4; ++i) {
;           const int d0 = min(max(dd0[i], 0), 128), d1 = min(max(dd1[i], 0), 128);
;           lg0[i] = s0[i] * SC + biasd[d0 * 32 + head];
;           lg1[i] = s1[i] * SC + biasd[d1 * 32 + head];
;         }
;       }
.LBB0_1007:
	s_bitcmp1_b32 s10, 0
	s_cselect_b32 s11, 0x11000, 0
	s_add_i32 s12, s5, s11
	s_lshl_b32 s13, s10, 5
	v_add3_u32 v2, s12, v168, v162
	ds_read_b128 v[234:237], v2
	ds_read_b128 v[238:241], v2 offset:8704
	ds_read_b128 v[242:245], v2 offset:64
	ds_read_b128 v[246:249], v2 offset:8768
	ds_read_b128 v[250:253], v2 offset:128
	ds_read_b128 v[188:191], v2 offset:8832
	v_or_b32_e32 v0, s13, v148
	v_lshl_add_u32 v3, v0, 1, s3
	s_waitcnt lgkmcnt(5)
	v_mfma_f32_16x16x32_bf16 v[140:143], v[234:237], v[4:7], 0
	ds_read_b128 v[234:237], v2 offset:192
	s_waitcnt lgkmcnt(5)
	v_mfma_f32_16x16x32_bf16 v[144:147], v[238:241], v[4:7], 0
	ds_read_b128 v[238:241], v2 offset:8896
	ds_read2_b64 v[184:187], v3 offset1:4
	s_waitcnt lgkmcnt(6)
	v_mfma_f32_16x16x32_bf16 v[140:143], v[242:245], v[8:11], v[140:143]
	ds_read_b128 v[242:245], v2 offset:256
	s_waitcnt lgkmcnt(6)
	v_mfma_f32_16x16x32_bf16 v[144:147], v[246:249], v[8:11], v[144:147]
	ds_read_b128 v[246:249], v2 offset:8960
	s_waitcnt lgkmcnt(6)
	v_mfma_f32_16x16x32_bf16 v[140:143], v[250:253], v[12:15], v[140:143]
	ds_read_b128 v[250:253], v2 offset:320
	s_waitcnt lgkmcnt(6)
	v_mfma_f32_16x16x32_bf16 v[144:147], v[188:191], v[12:15], v[144:147]
	ds_read_b128 v[188:191], v2 offset:9024
	s_waitcnt lgkmcnt(6)
	v_mfma_f32_16x16x32_bf16 v[140:143], v[234:237], v[16:19], v[140:143]
	ds_read_b128 v[234:237], v2 offset:384
	s_waitcnt lgkmcnt(6)
	v_mfma_f32_16x16x32_bf16 v[144:147], v[238:241], v[16:19], v[144:147]
	ds_read_b128 v[238:241], v2 offset:9088
	s_waitcnt lgkmcnt(5)
	v_mfma_f32_16x16x32_bf16 v[140:143], v[242:245], v[20:23], v[140:143]
	ds_read_b128 v[242:245], v2 offset:448
	s_waitcnt lgkmcnt(5)
	v_mfma_f32_16x16x32_bf16 v[144:147], v[246:249], v[20:23], v[144:147]
	ds_read_b128 v[246:249], v2 offset:9152
	s_waitcnt lgkmcnt(5)
	v_mfma_f32_16x16x32_bf16 v[140:143], v[250:253], v[24:27], v[140:143]
	s_waitcnt lgkmcnt(4)
	v_mfma_f32_16x16x32_bf16 v[144:147], v[188:191], v[24:27], v[144:147]
	s_waitcnt lgkmcnt(3)
	v_mfma_f32_16x16x32_bf16 v[140:143], v[234:237], v[28:31], v[140:143]
	s_waitcnt lgkmcnt(2)
	v_mfma_f32_16x16x32_bf16 v[144:147], v[238:241], v[28:31], v[144:147]
	s_waitcnt lgkmcnt(1)
	v_mfma_f32_16x16x32_bf16 v[140:143], v[242:245], v[32:35], v[140:143]
	s_waitcnt lgkmcnt(0)
	v_mfma_f32_16x16x32_bf16 v[144:147], v[246:249], v[32:35], v[144:147]
	s_branch .Lp4_softmax
.Lp4_softmax:
	s_waitcnt lgkmcnt(0)
	v_or_b32_e32 v0, s13, v148
	v_add_u32_e32 v192, s12, v163
	v_add3_u32 v192, v192, v164, v165
	v_sub_u32_sdwa v3, s14, v187 dst_sel:DWORD dst_unused:UNUSED_PAD src0_sel:DWORD src1_sel:WORD_1
	v_sub_u32_sdwa v136, s14, v184 dst_sel:DWORD dst_unused:UNUSED_PAD src0_sel:DWORD src1_sel:WORD_0
	v_sub_u32_sdwa v137, s14, v186 dst_sel:DWORD dst_unused:UNUSED_PAD src0_sel:DWORD src1_sel:WORD_0
	v_sub_u32_sdwa v134, s14, v184 dst_sel:DWORD dst_unused:UNUSED_PAD src0_sel:DWORD src1_sel:WORD_1
	v_sub_u32_sdwa v135, s14, v186 dst_sel:DWORD dst_unused:UNUSED_PAD src0_sel:DWORD src1_sel:WORD_1
	v_sub_u32_sdwa v132, s14, v185 dst_sel:DWORD dst_unused:UNUSED_PAD src0_sel:DWORD src1_sel:WORD_0
	v_sub_u32_sdwa v133, s14, v187 dst_sel:DWORD dst_unused:UNUSED_PAD src0_sel:DWORD src1_sel:WORD_0
	v_sub_u32_sdwa v2, s14, v185 dst_sel:DWORD dst_unused:UNUSED_PAD src0_sel:DWORD src1_sel:WORD_1
	v_min_i32_e32 v138, v134, v135
	v_min3_i32 v138, v136, v137, v138
	v_min_i32_e32 v139, v132, v133
	v_min_i32_e32 v193, v2, v3
	v_min3_i32 v138, v138, v139, v193
	v_cmp_gt_i32_e32 vcc, s16, v138
	s_cbranch_vccz .Lp4_far
	v_med3_i32 v136, v136, 0, v172
	v_med3_i32 v137, v137, 0, v172
	v_med3_i32 v132, v132, 0, v172
	v_med3_i32 v133, v133, 0, v172
	v_med3_i32 v2, v2, 0, v172
	v_med3_i32 v134, v134, 0, v172
	v_med3_i32 v135, v135, 0, v172
	v_med3_i32 v3, v3, 0, v172
	v_lshl_add_u32 v136, v136, 7, v169
	v_lshl_add_u32 v137, v137, 7, v169
	v_lshl_add_u32 v132, v132, 7, v169
	v_lshl_add_u32 v133, v133, 7, v169
	v_lshl_add_u32 v139, v2, 7, v169
	v_lshl_add_u32 v134, v134, 7, v169
	v_lshl_add_u32 v135, v135, 7, v169
	v_lshl_add_u32 v193, v3, 7, v169
	ds_read_b32 v2, v136
	ds_read_b32 v136, v137
	ds_read_b32 v132, v132
	ds_read_b32 v138, v133
	ds_read_b32 v133, v139
	ds_read_b32 v3, v134
	ds_read_b32 v139, v193
	ds_read_b32 v137, v135
	ds_read_b64_tr_b16 v[234:235], v192
	ds_read_b64_tr_b16 v[236:237], v192 offset:8704
	ds_read_b64_tr_b16 v[238:239], v192 offset:32
	ds_read_b64_tr_b16 v[240:241], v192 offset:8736
	ds_read_b64_tr_b16 v[242:243], v192 offset:64
	ds_read_b64_tr_b16 v[244:245], v192 offset:8768
	s_waitcnt lgkmcnt(6)
	v_pk_fma_f32 v[134:135], v[142:143], s[4:5], v[132:133] op_sel_hi:[1,0,1]
	v_pk_fma_f32 v[132:133], v[140:141], s[4:5], v[2:3] op_sel_hi:[1,0,1]
	v_pk_fma_f32 v[138:139], v[146:147], s[4:5], v[138:139] op_sel_hi:[1,0,1]
	v_pk_fma_f32 v[136:137], v[144:145], s[4:5], v[136:137] op_sel_hi:[1,0,1]
	ds_read_b64_tr_b16 v[246:247], v192 offset:96
	ds_read_b64_tr_b16 v[248:249], v192 offset:8800
	ds_read_b64_tr_b16 v[250:251], v192 offset:128
	ds_read_b64_tr_b16 v[252:253], v192 offset:8832
	ds_read_b64_tr_b16 v[188:189], v192 offset:160
	ds_read_b64_tr_b16 v[190:191], v192 offset:8864
	ds_read_b64_tr_b16 v[176:177], v192 offset:192
	ds_read_b64_tr_b16 v[178:179], v192 offset:8896
	s_branch .Lp4_lg
; __device__ __forceinline__ float pmax16(float x) { const u32x2s r = __builtin_amdgcn_permlane16_swap(__float_as_uint(x), __float_as_uint(x), false, false); return __builtin_amdgcn_fmed3f(__uint_as_float(r[0]), __uint_as_float(r[1]), __builtin_inff()); }
; __device__ __forceinline__ float pmax32(float x) { const u32x2s r = __builtin_amdgcn_permlane32_swap(__float_as_uint(x), __float_as_uint(x), false, false); return __builtin_amdgcn_fmed3f(__uint_as_float(r[0]), __uint_as_float(r[1]), __builtin_inff()); }
; __device__ __forceinline__ float vmax(float a, float b) { return __builtin_amdgcn_fmed3f(a, b, __builtin_inff()); }
; __device__ __forceinline__ void p4_attn(const Params& p, unsigned char* lds, int bid, int nb, bool dry) {
;     ...
;       if (__ballot(dmin < 128) == 0ull) {
;         const float bfar = biasd[128 * 32 + head];
; #pragma unroll
;         for (int i = 0; i < 4; ++i) { lg0[i] = s0[i] * SC + bfar; lg1[i] = s1[i] * SC + bfar; }
;       } else {
; #pragma unroll
;         for (int i = 0; i < 4; ++i) {
;           const int d0 = min(max(dd0[i], 0), 128), d1 = min(max(dd1[i], 0), 128);
;           lg0[i] = s0[i] * SC + biasd[d0 * 32 + head];
;           lg1[i] = s1[i] * SC + biasd[d1 * 32 + head];
;         }
;       }
; #pragma unroll
;       for (int i = 0; i < 4; ++i) {
;         if (!full) {
;           lg0[i] = (slotb + i < nk) ? lg0[i] : -1e30f;
;           lg1[i] = (slotb + 16 + i < nk) ? lg1[i] : -1e30f;
;         }
;         mx = vmax(mx, vmax(lg0[i], lg1[i]));
;       }
;       mx = pmax32(pmax16(mx));
;       float alpha = 1.f;
;       if (__ballot(mx > m_run + 8.f) != 0ull) {
;         const float m_new = vmax(m_run, mx); alpha = __builtin_amdgcn_exp2f(m_run - m_new); m_run = m_new;
; #pragma unroll
;         for (int ct = 0; ct < 16; ++ct) o[ct] *= alpha;
;       }
.Lp4_far:
	ds_read_b32 v2, v169 offset:16384
	ds_read_b64_tr_b16 v[234:235], v192
	ds_read_b64_tr_b16 v[236:237], v192 offset:8704
	ds_read_b64_tr_b16 v[238:239], v192 offset:32
	ds_read_b64_tr_b16 v[240:241], v192 offset:8736
	ds_read_b64_tr_b16 v[242:243], v192 offset:64
	ds_read_b64_tr_b16 v[244:245], v192 offset:8768
	ds_read_b64_tr_b16 v[246:247], v192 offset:96
	ds_read_b64_tr_b16 v[248:249], v192 offset:8800
	ds_read_b64_tr_b16 v[250:251], v192 offset:128
	ds_read_b64_tr_b16 v[252:253], v192 offset:8832
	ds_read_b64_tr_b16 v[188:189], v192 offset:160
	ds_read_b64_tr_b16 v[190:191], v192 offset:8864
	ds_read_b64_tr_b16 v[176:177], v192 offset:192
	ds_read_b64_tr_b16 v[178:179], v192 offset:8896
	s_waitcnt lgkmcnt(14)
	v_pk_fma_f32 v[134:135], v[142:143], s[4:5], v[2:3] op_sel_hi:[1,0,0]
	v_pk_fma_f32 v[132:133], v[140:141], s[4:5], v[2:3] op_sel_hi:[1,0,0]
	v_pk_fma_f32 v[138:139], v[146:147], s[4:5], v[2:3] op_sel_hi:[1,0,0]
	v_pk_fma_f32 v[136:137], v[144:145], s[4:5], v[2:3] op_sel_hi:[1,0,0]
.Lp4_lg:
	s_or_b32 s11, s13, 31
	s_cmp_gt_i32 s11, s15
	s_cbranch_scc0 .Lp4_max
	v_cmp_ge_i32_e32 vcc, s15, v0
	s_nop 1
	v_cndmask_b32_e32 v132, v173, v132, vcc
	v_or_b32_e32 v193, 16, v0
	v_cmp_ge_i32_e32 vcc, s15, v193
	s_nop 1
	v_cndmask_b32_e32 v136, v173, v136, vcc
	v_or_b32_e32 v193, 1, v0
	v_cmp_ge_i32_e32 vcc, s15, v193
	s_nop 1
	v_cndmask_b32_e32 v133, v173, v133, vcc
	v_or_b32_e32 v193, 17, v0
	v_cmp_ge_i32_e32 vcc, s15, v193
	s_nop 1
	v_cndmask_b32_e32 v137, v173, v137, vcc
	v_or_b32_e32 v193, 2, v0
	v_cmp_ge_i32_e32 vcc, s15, v193
	s_nop 1
	v_cndmask_b32_e32 v134, v173, v134, vcc
	v_or_b32_e32 v193, 18, v0
	v_cmp_ge_i32_e32 vcc, s15, v193
	s_nop 1
	v_cndmask_b32_e32 v138, v173, v138, vcc
	v_or_b32_e32 v193, 3, v0
	v_cmp_ge_i32_e32 vcc, s15, v193
	s_nop 1
	v_cndmask_b32_e32 v135, v173, v135, vcc
	v_or_b32_e32 v193, 19, v0
	v_cmp_ge_i32_e32 vcc, s15, v193
	s_nop 1
	v_cndmask_b32_e32 v139, v173, v139, vcc
.Lp4_max:
	v_max3_f32 v0, v132, v136, v133
	v_max3_f32 v140, v137, v134, v138
	v_max3_f32 v141, v135, v139, v173
	v_max3_f32 v0, v0, v140, v141
	v_mov_b32_e32 v144, v0
	s_nop 1
	v_permlane16_swap_b32_e32 v0, v144
	v_max_f32_e32 v0, v0, v144
	v_mov_b32_e32 v144, v0
	s_nop 1
	v_permlane32_swap_b32_e32 v0, v144
	v_max_f32_e32 v0, v0, v144
	v_add_f32_e32 v144, 0x41000000, v175
	v_cmp_gt_f32_e32 vcc, v0, v144
	s_cbranch_vccz .Lp4_norescale
	v_max_f32_e32 v144, v175, v0
	v_sub_f32_e32 v0, v175, v144
	v_exp_f32_e32 v0, v0
	v_mov_b32_e32 v175, v144
	v_pk_mul_f32 v[130:131], v[130:131], v[0:1] op_sel_hi:[1,0]
	v_pk_mul_f32 v[128:129], v[128:129], v[0:1] op_sel_hi:[1,0]
	v_pk_mul_f32 v[126:127], v[126:127], v[0:1] op_sel_hi:[1,0]
	v_pk_mul_f32 v[124:125], v[124:125], v[0:1] op_sel_hi:[1,0]
	v_pk_mul_f32 v[122:123], v[122:123], v[0:1] op_sel_hi:[1,0]
	v_pk_mul_f32 v[120:121], v[120:121], v[0:1] op_sel_hi:[1,0]
	v_pk_mul_f32 v[118:119], v[118:119], v[0:1] op_sel_hi:[1,0]
	v_pk_mul_f32 v[116:117], v[116:117], v[0:1] op_sel_hi:[1,0]
	v_pk_mul_f32 v[114:115], v[114:115], v[0:1] op_sel_hi:[1,0]
	v_pk_mul_f32 v[112:113], v[112:113], v[0:1] op_sel_hi:[1,0]
	v_pk_mul_f32 v[106:107], v[106:107], v[0:1] op_sel_hi:[1,0]
	v_pk_mul_f32 v[104:105], v[104:105], v[0:1] op_sel_hi:[1,0]
	v_pk_mul_f32 v[98:99], v[98:99], v[0:1] op_sel_hi:[1,0]
	v_pk_mul_f32 v[96:97], v[96:97], v[0:1] op_sel_hi:[1,0]
	v_pk_mul_f32 v[94:95], v[94:95], v[0:1] op_sel_hi:[1,0]
	v_pk_mul_f32 v[92:93], v[92:93], v[0:1] op_sel_hi:[1,0]
	v_pk_mul_f32 v[82:83], v[82:83], v[0:1] op_sel_hi:[1,0]
	v_pk_mul_f32 v[80:81], v[80:81], v[0:1] op_sel_hi:[1,0]
	v_pk_mul_f32 v[78:79], v[78:79], v[0:1] op_sel_hi:[1,0]
	v_pk_mul_f32 v[76:77], v[76:77], v[0:1] op_sel_hi:[1,0]
	v_pk_mul_f32 v[74:75], v[74:75], v[0:1] op_sel_hi:[1,0]
	v_pk_mul_f32 v[72:73], v[72:73], v[0:1] op_sel_hi:[1,0]
	v_pk_mul_f32 v[66:67], v[66:67], v[0:1] op_sel_hi:[1,0]
	v_pk_mul_f32 v[64:65], v[64:65], v[0:1] op_sel_hi:[1,0]
	v_pk_mul_f32 v[58:59], v[58:59], v[0:1] op_sel_hi:[1,0]
	v_pk_mul_f32 v[56:57], v[56:57], v[0:1] op_sel_hi:[1,0]
	v_pk_mul_f32 v[54:55], v[54:55], v[0:1] op_sel_hi:[1,0]
	v_pk_mul_f32 v[52:53], v[52:53], v[0:1] op_sel_hi:[1,0]
	v_pk_mul_f32 v[42:43], v[42:43], v[0:1] op_sel_hi:[1,0]
	v_pk_mul_f32 v[40:41], v[40:41], v[0:1] op_sel_hi:[1,0]
	v_pk_mul_f32 v[38:39], v[38:39], v[0:1] op_sel_hi:[1,0]
	v_pk_mul_f32 v[36:37], v[36:37], v[0:1] op_sel_hi:[1,0]
	s_branch .Lp4_exp

; #define LAS __attribute__((address_space(3)))
; __device__ __forceinline__ u32x4 pack8(f32x4 a, f32x4 b) { u32x4 w; w[0] = cvt_pk_bf16(a[0], a[1]); w[1] = cvt_pk_bf16(a[2], a[3]); w[2] = cvt_pk_bf16(b[0], b[1]); w[3] = cvt_pk_bf16(b[2], b[3]); return w; }
; __device__ __forceinline__ void p4_attn(const Params& p, unsigned char* lds, int bid, int nb, bool dry) {
;     ...
;       float ps = 0.f; f32x4 p0, p1;
; #pragma unroll
;       for (int i = 0; i < 4; ++i) { p0[i] = __builtin_amdgcn_exp2f(lg0[i] - m_run); p1[i] = __builtin_amdgcn_exp2f(lg1[i] - m_run); ps += p0[i] + p1[i]; }
;       l_run = l_run * alpha + ps;
;       const u32x4 pw = pack8(p0, p1);
;       bf16x8 pb; { union { u32x4 u; bf16x8 v; } cv; cv.u = pw; pb = cv.v; }
;       LAS unsigned char* trb = cb + troff;
; #pragma unroll
;       for (int ct = 0; ct < 16; ++ct) {
;         const s16x4 ta = __builtin_amdgcn_ds_read_tr16_b64_v4i16((LAS s16x4*)(trb + 32 * ct));
;         const s16x4 tb = __builtin_amdgcn_ds_read_tr16_b64_v4i16((LAS s16x4*)(trb + 16 * CROW + 32 * ct));
;         const bf16x8 a = {ta[0], ta[1], ta[2], ta[3], tb[0], tb[1], tb[2], tb[3]};
;         o[ct] = __builtin_amdgcn_mfma_f32_16x16x32_bf16(a, pb, o[ct], 0, 0, 0);
;       }
;       epoch += 2u; pair_sync(pcnt, epoch, lane);
.Lp4_exp:
	v_sub_f32_e32 v2, v132, v175
	v_sub_f32_e32 v3, v136, v175
	v_sub_f32_e32 v132, v133, v175
	v_sub_f32_e32 v133, v137, v175
	v_sub_f32_e32 v136, v138, v175
	v_sub_f32_e32 v137, v139, v175
	v_sub_f32_e32 v134, v134, v175
	v_sub_f32_e32 v135, v135, v175
	v_exp_f32_e32 v2, v2
	v_exp_f32_e32 v3, v3
	v_exp_f32_e32 v132, v132
	v_exp_f32_e32 v133, v133
	v_exp_f32_e32 v134, v134
	v_exp_f32_e32 v136, v136
	v_exp_f32_e32 v135, v135
	v_exp_f32_e32 v137, v137
	v_cvt_pk_bf16_f32 v138, v2, v132
	v_cvt_pk_bf16_f32 v139, v134, v135
	v_cvt_pk_bf16_f32 v140, v3, v133
	v_cvt_pk_bf16_f32 v141, v136, v137
	s_nop 1
	s_waitcnt lgkmcnt(12)
	v_mfma_f32_16x16x32_bf16 v[128:131], v[234:237], v[138:141], v[128:131]
	ds_read_b64_tr_b16 v[180:181], v192 offset:224
	ds_read_b64_tr_b16 v[182:183], v192 offset:8928
	s_waitcnt lgkmcnt(12)
	v_mfma_f32_16x16x32_bf16 v[124:127], v[238:241], v[138:141], v[124:127]
	ds_read_b64_tr_b16 v[234:235], v192 offset:256
	ds_read_b64_tr_b16 v[236:237], v192 offset:8960
	s_waitcnt lgkmcnt(12)
	v_mfma_f32_16x16x32_bf16 v[120:123], v[242:245], v[138:141], v[120:123]
	ds_read_b64_tr_b16 v[238:239], v192 offset:288
	ds_read_b64_tr_b16 v[240:241], v192 offset:8992
	s_waitcnt lgkmcnt(12)
	v_mfma_f32_16x16x32_bf16 v[116:119], v[246:249], v[138:141], v[116:119]
	ds_read_b64_tr_b16 v[242:243], v192 offset:320
	ds_read_b64_tr_b16 v[244:245], v192 offset:9024
	s_waitcnt lgkmcnt(12)
	v_mfma_f32_16x16x32_bf16 v[112:115], v[250:253], v[138:141], v[112:115]
	ds_read_b64_tr_b16 v[246:247], v192 offset:352
	ds_read_b64_tr_b16 v[248:249], v192 offset:9056
	s_waitcnt lgkmcnt(12)
	v_mfma_f32_16x16x32_bf16 v[104:107], v[188:191], v[138:141], v[104:107]
	ds_read_b64_tr_b16 v[250:251], v192 offset:384
	ds_read_b64_tr_b16 v[252:253], v192 offset:9088
	s_waitcnt lgkmcnt(12)
	v_mfma_f32_16x16x32_bf16 v[96:99], v[176:179], v[138:141], v[96:99]
	ds_read_b64_tr_b16 v[188:189], v192 offset:416
	ds_read_b64_tr_b16 v[190:191], v192 offset:9120
	s_waitcnt lgkmcnt(12)
	v_mfma_f32_16x16x32_bf16 v[92:95], v[180:183], v[138:141], v[92:95]
	ds_read_b64_tr_b16 v[176:177], v192 offset:448
	ds_read_b64_tr_b16 v[178:179], v192 offset:9152
	s_waitcnt lgkmcnt(12)
	v_mfma_f32_16x16x32_bf16 v[80:83], v[234:237], v[138:141], v[80:83]
	ds_read_b64_tr_b16 v[180:181], v192 offset:480
	ds_read_b64_tr_b16 v[182:183], v192 offset:9184
	s_waitcnt lgkmcnt(12)
	v_mfma_f32_16x16x32_bf16 v[76:79], v[238:241], v[138:141], v[76:79]
	s_waitcnt lgkmcnt(10)
	v_mfma_f32_16x16x32_bf16 v[72:75], v[242:245], v[138:141], v[72:75]
	s_waitcnt lgkmcnt(8)
	v_mfma_f32_16x16x32_bf16 v[64:67], v[246:249], v[138:141], v[64:67]
	s_waitcnt lgkmcnt(6)
	v_mfma_f32_16x16x32_bf16 v[56:59], v[250:253], v[138:141], v[56:59]
	s_waitcnt lgkmcnt(4)
	v_mfma_f32_16x16x32_bf16 v[52:55], v[188:191], v[138:141], v[52:55]
	s_waitcnt lgkmcnt(2)
	v_mfma_f32_16x16x32_bf16 v[40:43], v[176:179], v[138:141], v[40:43]
	s_waitcnt lgkmcnt(0)
	v_mfma_f32_16x16x32_bf16 v[36:39], v[180:183], v[138:141], v[36:39]
	s_and_saveexec_b64 s[10:11], s[8:9]
	s_cbranch_execz .LBB0_1017
	s_mov_b64 s[12:13], exec
	v_mbcnt_lo_u32_b32 v138, s12, 0
	v_mbcnt_hi_u32_b32 v138, s13, v138
	v_cmp_eq_u32_e32 vcc, 0, v138
	s_and_b64 s[24:25], exec, vcc
	s_mov_b64 exec, s[24:25]
	s_bcnt1_i32_b64 s12, s[12:13]
	v_mov_b32_e32 v138, s2
	v_mov_b32_e32 v139, s12
	ds_add_u32 v138, v139
